# main row phase software-pipelined: next step's 8 row loads prefetched into a second register set during the current step (non-pooled phases), g_post parameters loaded once per phase
# speedup vs baseline: 1.0073x; 1.0073x over previous
; __device__ __forceinline__ KP kp_fresh(KP k) { asm volatile("" : "+s"(k)); return k; }
; __device__ __forceinline__ int tid_fresh(int wid) { return wid * 64 + lane_id(); }
; __device__ __forceinline__ bf16* hrow16(unsigned char* ws, int r) { return (bf16*)(ws + WS_H16) + ((size_t)r << 10); }
; __device__ __forceinline__ void unpack8(const u32x4 w, float* v) { v[0] = bflo(w.x); v[1] = bfhi(w.x); v[2] = bflo(w.y); v[3] = bfhi(w.y); v[4] = bflo(w.z); v[5] = bfhi(w.z); v[6] = bflo(w.w); v[7] = bfhi(w.w); }
; __device__ __forceinline__ void row_res(KP kp, int gpost_in, int layer, bool has_next, int wid0, int row0, int row1, int b0, int nb, int tailp, bool pooled) {
;     kp = kp_fresh(kp); const int tid = tid_fresh(wid0); const int lane = tid & 63, wid = tid >> 6;
;     unsigned char* ws = kp->ws; float* out = kp->out; const bf16* MX = (const bf16*)(ws + WS_MX); float* rsd = (float*)(ws + WS_RSTD);
;     const float* g_post = kp->in[gpost_in] + layer * DM;
;     for (int base = row0 + ((int)blockIdx.x - b0) * 16 + wid; base < row1; base += nb * 16) {
;         float m[2][2][8], h[2][2][8]; float ss[2] = {0.f, 0.f};
; #pragma unroll
;         for (int r = 0; r < 2; ++r) { const int row = base + 8 * r; bf16* hp = hrow16(ws, row);
; #pragma unroll
;             for (int c = 0; c < 2; ++c) {
;                 if (tailp) { const bf16* t0 = (const bf16*)(ws + WS_MXT) + (size_t)(row - 128 * 256) * DM + c * 512 + lane * 8; unpack8(*(const u32x4*)t0, m[r][c]);
;     ...
;             for (int c = 0; c < 2; ++c) { const int col = c * 512 + lane * 8; const f32x4 ga = *(const f32x4*)(g_post + col), gb = *(const f32x4*)(g_post + col + 4);
.LBB0_773:
	s_or_b64 exec, exec, s[2:3]
	s_and_b64 s[2:3], s[28:29], exec
	v_readlane_b32 s2, v255, 49
	v_readlane_b32 s3, v255, 50
	s_cselect_b32 s17, 3, 5
	s_nor_b64 s[34:35], s[2:3], s[28:29]
	v_readlane_b32 s2, v255, 51
	v_readlane_b32 s3, v255, 52
	s_and_b64 s[2:3], s[2:3], s[28:29]
	s_cselect_b32 s18, 4, 16
	s_cmp_ge_i32 s33, s18
	s_mov_b64 s[2:3], -1
	s_waitcnt lgkmcnt(0)
	s_barrier
	s_cbranch_scc0 .LBB0_822
	s_mov_b64 s[2:3], s[88:89]
	v_mbcnt_lo_u32_b32 v1, -1, 0
	v_mbcnt_hi_u32_b32 v1, -1, v1
	s_sub_i32 s4, s33, s18
	v_add_u32_e32 v2, s61, v1
	v_ashrrev_i32_e32 v2, 6, v2
	v_lshl_add_u32 v38, s4, 4, v2
	s_mov_b32 s4, 0x8000
	v_cmp_gt_i32_e32 vcc, s4, v38
	s_and_saveexec_b64 s[44:45], vcc
	s_cbranch_execz .LBB0_821
	s_load_dwordx4 s[8:11], s[2:3], 0x90
	v_readlane_b32 s4, v255, 51
	v_readlane_b32 s5, v255, 52
	s_and_b64 s[4:5], s[4:5], s[28:29]
	s_xor_b64 s[78:79], s[4:5], -1
	s_waitcnt lgkmcnt(0)
	s_add_u32 s92, s10, 0x180000
	s_addc_u32 s93, s11, 0
	s_lshl_b32 s4, s17, 3
	s_load_dwordx2 s[2:3], s[2:3], s4 offset:0x0
	v_readlane_b32 s4, v255, 53
	v_readlane_b32 s5, v255, 54
	v_and_b32_e32 v3, 63, v1
	s_sub_i32 s14, s38, s18
	s_lshl_b64 s[4:5], s[4:5], 2
	v_lshlrev_b32_e32 v4, 4, v3
	s_waitcnt lgkmcnt(0)
	s_add_u32 s4, s2, s4
	v_mov_b32_e32 v5, v0
	s_addc_u32 s5, s3, s5
	s_waitcnt vmcnt(2)
	v_lshl_add_u64 v[6:7], s[10:11], 0, v[4:5]
	s_mov_b64 s[2:3], 0x18f74000
	v_lshl_add_u64 v[42:43], v[6:7], 0, s[2:3]
	s_mov_b64 s[2:3], 0x10e74000
	v_lshl_add_u64 v[44:45], v[6:7], 0, s[2:3]
	v_bfe_u32 v6, v1, 5, 1
	v_lshlrev_b32_e64 v1, v6, 2
	v_lshlrev_b32_e64 v41, v6, 8
	v_lshlrev_b32_e32 v6, 2, v3
	s_lshl_b32 s46, s14, 4
	v_xor_b32_e32 v101, 0x80, v6
	v_xor_b32_e32 v102, 64, v6
	v_xor_b32_e32 v103, 32, v6
	v_xor_b32_e32 v104, 16, v6
	v_xor_b32_e32 v105, 8, v6
	v_xor_b32_e32 v106, 4, v6
	v_lshlrev_b32_e32 v6, 5, v3
	v_mov_b32_e32 v7, v0
	v_lshl_add_u64 v[46:47], s[4:5], 0, v[6:7]
	s_add_u32 s4, s10, 0x10e73800
	v_ashrrev_i32_e32 v39, 31, v38
	s_addc_u32 s5, s11, 0
	v_lshlrev_b64 v[6:7], 11, v[38:39]
	s_ashr_i32 s47, s46, 31
	v_or_b32_e32 v6, v6, v4
	s_lshl_b64 s[58:59], s[46:47], 11
	v_lshl_add_u64 v[48:49], s[4:5], 0, v[6:7]
	s_add_u32 s10, s10, 0x10e73c00
	v_lshl_add_u64 v[52:53], s[4:5], 0, v[4:5]
	v_readlane_b32 s4, v255, 31
	s_addc_u32 s11, s11, 0
	v_lshlrev_b32_e32 v40, 3, v3
	v_add_u32_e32 v2, s4, v2
	s_lshl_b32 s4, s18, 4
	v_cmp_eq_u32_e64 s[2:3], 0, v3
	v_lshl_add_u64 v[50:51], s[10:11], 0, v[6:7]
	v_subrev_u32_e32 v54, s4, v2
	v_lshl_add_u64 v[56:57], s[10:11], 0, v[4:5]
	s_mov_b64 s[10:11], 0
	global_load_dwordx4 v[152:155], v[46:47], off
	global_load_dwordx4 v[156:159], v[46:47], off offset:16
	global_load_dwordx4 v[160:163], v[46:47], off offset:2048
	global_load_dwordx4 v[164:167], v[46:47], off offset:2064
	s_cmp_eq_u64 s[78:79], 0
	s_cbranch_scc1 .Lrp_predone
	v_ashrrev_i32_e32 v39, 31, v38
	v_lshlrev_b64 v[2:3], 11, v[38:39]
	v_lshl_add_u64 v[4:5], v[44:45], 0, v[2:3]
	v_add_u32_e32 v116, 8, v38
	v_lshl_add_u64 v[170:171], v[42:43], 0, v[2:3]
	v_ashrrev_i32_e32 v117, 31, v116
	global_load_dwordx4 v[120:123], v[4:5], off
	global_load_dwordx4 v[124:127], v[4:5], off offset:1024
	v_lshlrev_b64 v[116:117], 11, v[116:117]
	global_load_dwordx4 v[136:139], v[170:171], off
	global_load_dwordx4 v[140:143], v[170:171], off offset:1024
	v_lshl_add_u64 v[168:169], v[44:45], 0, v[116:117]
	v_lshl_add_u64 v[172:173], v[42:43], 0, v[116:117]
	global_load_dwordx4 v[128:131], v[168:169], off
	global_load_dwordx4 v[132:135], v[168:169], off offset:1024
	global_load_dwordx4 v[144:147], v[172:173], off
	global_load_dwordx4 v[148:151], v[172:173], off offset:1024
.Lrp_predone:
	s_waitcnt vmcnt(0)
	s_branch .LBB0_778

; __device__ __forceinline__ bf16* hrow16(unsigned char* ws, int r) { return (bf16*)(ws + WS_H16) + ((size_t)r << 10); }
; __device__ __forceinline__ void unpack8(const u32x4 w, float* v) { v[0] = bflo(w.x); v[1] = bfhi(w.x); v[2] = bflo(w.y); v[3] = bfhi(w.y); v[4] = bflo(w.z); v[5] = bfhi(w.z); v[6] = bflo(w.w); v[7] = bfhi(w.w); }
; __device__ __forceinline__ void row_res(KP kp, int gpost_in, int layer, bool has_next, int wid0, int row0, int row1, int b0, int nb, int tailp, bool pooled) {
;     ...
;     for (int base = row0 + ((int)blockIdx.x - b0) * 16 + wid; base < row1; base += nb * 16) {
;         float m[2][2][8], h[2][2][8]; float ss[2] = {0.f, 0.f};
; #pragma unroll
;         for (int r = 0; r < 2; ++r) { const int row = base + 8 * r; bf16* hp = hrow16(ws, row);
; #pragma unroll
;             for (int c = 0; c < 2; ++c) {
;                 if (tailp) { const bf16* t0 = (const bf16*)(ws + WS_MXT) + (size_t)(row - 128 * 256) * DM + c * 512 + lane * 8; unpack8(*(const u32x4*)t0, m[r][c]);
;                     for (int q = 1; q < tailp; ++q) { float m2[8]; unpack8(*(const u32x4*)(t0 + (size_t)q * 256 * 1024), m2);
; #pragma unroll
;                         for (int j = 0; j < 8; ++j) m[r][c][j] += m2[j]; } }
;                 else if (pooled) { const int t = row % LL, win = 2 << (c * 2 + (lane >> 5)), cnt = (t + 1) < win ? (t + 1) : win; const bf16* zp = MX + (size_t)row * DM + c * 512 + lane * 8;
;                     float z0[8], sum[8]; unpack8(*(const u32x4*)zp, z0);
; #pragma unroll
;                     for (int j = 0; j < 8; ++j) sum[j] = z0[j];
;                     for (int d = 1; d < cnt; ++d) { float zd[8]; unpack8(*(const u32x4*)(zp - (size_t)d * DM), zd);
; #pragma unroll
;                         for (int j = 0; j < 8; ++j) sum[j] += zd[j]; }
;                     const float inv = 1.0f / (float)cnt;
; #pragma unroll
;                     for (int j = 0; j < 8; ++j) m[r][c][j] = sum[j] * inv - z0[j]; }
;                 else { const u32x4 w = *(const u32x4*)(MX + (size_t)row * DM + c * 512 + lane * 8); unpack8(w, m[r][c]); }
;                 unpack8(*(const u32x4*)(hp + c * 512 + lane * 8), h[r][c]);
.LBB0_778:
	v_ashrrev_i32_e32 v39, 31, v38
	v_lshlrev_b64 v[2:3], 11, v[38:39]
	s_cmp_eq_u64 s[78:79], 0
	s_cbranch_scc1 .Lrp_ptop
	v_add_u32_e32 v116, s46, v38
	v_min_i32_e32 v116, 0x7ff7, v116
	v_ashrrev_i32_e32 v117, 31, v116
	v_lshlrev_b64 v[116:117], 11, v[116:117]
	v_lshl_add_u64 v[4:5], v[44:45], 0, v[116:117]
	v_lshl_add_u64 v[170:171], v[42:43], 0, v[116:117]
	s_mov_b64 s[94:95], 0x4000
	v_lshl_add_u64 v[168:169], v[4:5], 0, s[94:95]
	v_lshl_add_u64 v[172:173], v[170:171], 0, s[94:95]
	global_load_dwordx4 v[174:177], v[4:5], off
	global_load_dwordx4 v[178:181], v[4:5], off offset:1024
	global_load_dwordx4 v[190:193], v[170:171], off
	global_load_dwordx4 v[194:197], v[170:171], off offset:1024
	global_load_dwordx4 v[182:185], v[168:169], off
	global_load_dwordx4 v[186:189], v[168:169], off offset:1024
	global_load_dwordx4 v[198:201], v[172:173], off
	global_load_dwordx4 v[202:205], v[172:173], off offset:1024
	s_branch .Lrp_tdone
.Lrp_ptop:
	v_lshl_add_u64 v[4:5], v[44:45], 0, v[2:3]
	v_add_u32_e32 v116, 8, v38
	v_lshl_add_u64 v[170:171], v[42:43], 0, v[2:3]
	v_ashrrev_i32_e32 v117, 31, v116
	global_load_dwordx4 v[120:123], v[4:5], off
	global_load_dwordx4 v[124:127], v[4:5], off offset:1024
	v_lshlrev_b64 v[116:117], 11, v[116:117]
	global_load_dwordx4 v[136:139], v[170:171], off
	global_load_dwordx4 v[140:143], v[170:171], off offset:1024
	v_lshl_add_u64 v[168:169], v[44:45], 0, v[116:117]
	v_lshl_add_u64 v[172:173], v[42:43], 0, v[116:117]
	global_load_dwordx4 v[128:131], v[168:169], off
	global_load_dwordx4 v[132:135], v[168:169], off offset:1024
	global_load_dwordx4 v[144:147], v[172:173], off
	global_load_dwordx4 v[148:151], v[172:173], off offset:1024
	s_waitcnt vmcnt(0)
.Lrp_tdone:
	s_mov_b64 s[4:5], -1
	s_and_b64 vcc, exec, s[78:79]
	v_mov_b64_e32 v[6:7], v[120:121]
	v_mov_b64_e32 v[8:9], v[122:123]
	v_lshlrev_b32_e32 v22, 16, v6
	s_waitcnt lgkmcnt(0)
	v_and_b32_e32 v23, 0xffff0000, v6
	v_lshlrev_b32_e32 v24, 16, v7
	v_and_b32_e32 v25, 0xffff0000, v7
	v_lshlrev_b32_e32 v26, 16, v8
	v_and_b32_e32 v27, 0xffff0000, v8
	v_lshlrev_b32_e32 v28, 16, v9
	v_and_b32_e32 v29, 0xffff0000, v9
	s_cbranch_vccz .LBB0_780
	s_mov_b64 s[4:5], 0

; __device__ __forceinline__ void unpack8(const u32x4 w, float* v) { v[0] = bflo(w.x); v[1] = bfhi(w.x); v[2] = bflo(w.y); v[3] = bfhi(w.y); v[4] = bflo(w.z); v[5] = bfhi(w.z); v[6] = bflo(w.w); v[7] = bfhi(w.w); }
; __device__ __forceinline__ void row_res(KP kp, int gpost_in, int layer, bool has_next, int wid0, int row0, int row1, int b0, int nb, int tailp, bool pooled) {
;     ...
;                 else { const u32x4 w = *(const u32x4*)(MX + (size_t)row * DM + c * 512 + lane * 8); unpack8(w, m[r][c]); }
;                 unpack8(*(const u32x4*)(hp + c * 512 + lane * 8), h[r][c]);
; #pragma unroll
;                 for (int j = 0; j < 8; ++j) ss[r] += m[r][c][j] * m[r][c][j]; } }
.LBB0_786:
	v_mov_b64_e32 v[6:7], v[124:125]
	v_mov_b64_e32 v[8:9], v[126:127]
	v_lshl_add_u64 v[60:61], v[42:43], 0, v[2:3]
	v_mov_b64_e32 v[2:3], v[136:137]
	v_mov_b64_e32 v[4:5], v[138:139]
	v_cndmask_b32_e64 v10, 0, 1, s[78:79]
	s_mov_b64 s[14:15], -1
	v_cmp_ne_u32_e64 s[4:5], 1, v10
	s_andn2_b64 vcc, exec, s[78:79]
	v_lshlrev_b32_e32 v30, 16, v6
	v_and_b32_e32 v31, 0xffff0000, v6
	v_lshlrev_b32_e32 v32, 16, v7
	v_and_b32_e32 v33, 0xffff0000, v7
	v_lshlrev_b32_e32 v34, 16, v8
	v_and_b32_e32 v35, 0xffff0000, v8
	v_lshlrev_b32_e32 v36, 16, v9
	v_and_b32_e32 v37, 0xffff0000, v9
	s_cbranch_vccnz .LBB0_788
	s_mov_b64 s[14:15], 0

; __device__ __forceinline__ void unpack8(const u32x4 w, float* v) { v[0] = bflo(w.x); v[1] = bfhi(w.x); v[2] = bflo(w.y); v[3] = bfhi(w.y); v[4] = bflo(w.z); v[5] = bfhi(w.z); v[6] = bflo(w.w); v[7] = bfhi(w.w); }
; __device__ __forceinline__ void row_res(KP kp, int gpost_in, int layer, bool has_next, int wid0, int row0, int row1, int b0, int nb, int tailp, bool pooled) {
;     ...
;                 else { const u32x4 w = *(const u32x4*)(MX + (size_t)row * DM + c * 512 + lane * 8); unpack8(w, m[r][c]); }
;                 unpack8(*(const u32x4*)(hp + c * 512 + lane * 8), h[r][c]);
; #pragma unroll
;                 for (int j = 0; j < 8; ++j) ss[r] += m[r][c][j] * m[r][c][j]; } }
.LBB0_794:
	v_add_u32_e32 v62, 8, v38
	v_ashrrev_i32_e32 v63, 31, v62
	v_lshlrev_b64 v[10:11], 11, v[62:63]
	v_lshl_add_u64 v[12:13], v[44:45], 0, v[10:11]
	v_mov_b64_e32 v[14:15], v[128:129]
	v_mov_b64_e32 v[16:17], v[130:131]
	v_mov_b64_e32 v[6:7], v[140:141]
	v_mov_b64_e32 v[8:9], v[142:143]
	s_mov_b64 s[14:15], -1
	s_and_b64 vcc, exec, s[4:5]
	v_lshlrev_b32_e32 v68, 16, v14
	v_and_b32_e32 v69, 0xffff0000, v14
	v_lshlrev_b32_e32 v70, 16, v15
	v_and_b32_e32 v71, 0xffff0000, v15
	v_lshlrev_b32_e32 v72, 16, v16
	v_and_b32_e32 v73, 0xffff0000, v16
	v_lshlrev_b32_e32 v74, 16, v17
	v_and_b32_e32 v75, 0xffff0000, v17
	s_cbranch_vccnz .LBB0_796
	s_mov_b64 s[14:15], 0

; __device__ __forceinline__ void unpack8(const u32x4 w, float* v) { v[0] = bflo(w.x); v[1] = bfhi(w.x); v[2] = bflo(w.y); v[3] = bfhi(w.y); v[4] = bflo(w.z); v[5] = bfhi(w.z); v[6] = bflo(w.w); v[7] = bfhi(w.w); }
; __device__ __forceinline__ void row_res(KP kp, int gpost_in, int layer, bool has_next, int wid0, int row0, int row1, int b0, int nb, int tailp, bool pooled) {
;     ...
;                 else { const u32x4 w = *(const u32x4*)(MX + (size_t)row * DM + c * 512 + lane * 8); unpack8(w, m[r][c]); }
;                 unpack8(*(const u32x4*)(hp + c * 512 + lane * 8), h[r][c]);
; #pragma unroll
;                 for (int j = 0; j < 8; ++j) ss[r] += m[r][c][j] * m[r][c][j]; } }
.LBB0_802:
	v_mov_b64_e32 v[16:17], v[132:133]
	v_mov_b64_e32 v[18:19], v[134:135]
	v_lshl_add_u64 v[66:67], v[42:43], 0, v[10:11]
	v_mov_b64_e32 v[10:11], v[144:145]
	v_mov_b64_e32 v[12:13], v[146:147]
	s_mov_b64 s[14:15], -1
	s_and_b64 vcc, exec, s[4:5]
	v_lshlrev_b32_e32 v82, 16, v16
	v_and_b32_e32 v83, 0xffff0000, v16
	v_lshlrev_b32_e32 v80, 16, v17
	v_and_b32_e32 v81, 0xffff0000, v17
	v_lshlrev_b32_e32 v78, 16, v18
	v_and_b32_e32 v79, 0xffff0000, v18
	v_lshlrev_b32_e32 v76, 16, v19
	v_and_b32_e32 v77, 0xffff0000, v19
	s_cbranch_vccnz .LBB0_804
	s_mov_b64 s[14:15], 0

; __device__ __forceinline__ float lane_xchg_(float v, int srclane) { return __builtin_bit_cast(float, __builtin_amdgcn_ds_bpermute(srclane << 2, __builtin_bit_cast(int, v))); }
; __device__ __forceinline__ void unpack8(const u32x4 w, float* v) { v[0] = bflo(w.x); v[1] = bfhi(w.x); v[2] = bflo(w.y); v[3] = bfhi(w.y); v[4] = bflo(w.z); v[5] = bfhi(w.z); v[6] = bflo(w.w); v[7] = bfhi(w.w); }
; __device__ __forceinline__ void row_res(KP kp, int gpost_in, int layer, bool has_next, int wid0, int row0, int row1, int b0, int nb, int tailp, bool pooled) {
;     ...
;                 unpack8(*(const u32x4*)(hp + c * 512 + lane * 8), h[r][c]);
; #pragma unroll
;                 for (int j = 0; j < 8; ++j) ss[r] += m[r][c][j] * m[r][c][j]; } }
; #pragma unroll
;         for (int o = 32; o > 0; o >>= 1) { const float a = lane_xchg_(ss[0], lane ^ o), b = lane_xchg_(ss[1], lane ^ o); ss[0] += a; ss[1] += b; }
.LBB0_810:
	v_lshlrev_b32_e32 v84, 16, v10
	v_and_b32_e32 v85, 0xffff0000, v10
	v_lshlrev_b32_e32 v86, 16, v11
	v_and_b32_e32 v87, 0xffff0000, v11
	v_pk_mul_f32 v[10:11], v[22:23], v[22:23]
	v_lshlrev_b32_e32 v88, 16, v12
	v_and_b32_e32 v89, 0xffff0000, v12
	v_lshlrev_b32_e32 v90, 16, v13
	v_and_b32_e32 v91, 0xffff0000, v13
	v_pk_mul_f32 v[12:13], v[24:25], v[24:25]
	v_add_f32_e32 v10, v11, v10
	v_pk_mul_f32 v[14:15], v[68:69], v[68:69]
	v_add_f32_e32 v10, v12, v10
	v_pk_mul_f32 v[16:17], v[70:71], v[70:71]
	v_pk_mul_f32 v[108:109], v[26:27], v[26:27]
	v_add_f32_e32 v10, v13, v10
	v_add_f32_e32 v14, v15, v14
	v_add_f32_e32 v10, v108, v10
	v_add_f32_e32 v14, v16, v14
	v_pk_mul_f32 v[18:19], v[72:73], v[72:73]
	v_pk_mul_f32 v[110:111], v[28:29], v[28:29]
	v_add_f32_e32 v10, v109, v10
	v_add_f32_e32 v14, v17, v14
	v_add_f32_e32 v10, v110, v10
	v_add_f32_e32 v14, v18, v14
	v_pk_mul_f32 v[20:21], v[74:75], v[74:75]
	v_lshlrev_b32_e32 v92, 16, v6
	v_and_b32_e32 v93, 0xffff0000, v6
	v_lshlrev_b32_e32 v94, 16, v7
	v_and_b32_e32 v95, 0xffff0000, v7
	v_pk_mul_f32 v[6:7], v[30:31], v[30:31]
	v_add_f32_e32 v10, v111, v10
	v_add_f32_e32 v14, v19, v14
	v_add_f32_e32 v6, v10, v6
	v_add_f32_e32 v14, v20, v14
	v_lshlrev_b32_e32 v98, 16, v8
	v_and_b32_e32 v99, 0xffff0000, v8
	v_lshlrev_b32_e32 v96, 16, v9
	v_and_b32_e32 v97, 0xffff0000, v9
	v_pk_mul_f32 v[8:9], v[32:33], v[32:33]
	v_add_f32_e32 v6, v7, v6
	v_pk_mul_f32 v[108:109], v[82:83], v[82:83]
	v_add_f32_e32 v14, v21, v14
	v_add_f32_e32 v6, v8, v6
	v_add_f32_e32 v14, v14, v108
	v_pk_mul_f32 v[112:113], v[34:35], v[34:35]
	v_add_f32_e32 v6, v9, v6
	v_pk_mul_f32 v[110:111], v[80:81], v[80:81]
	v_add_f32_e32 v14, v109, v14
	v_add_f32_e32 v6, v112, v6
	v_add_f32_e32 v14, v110, v14
	v_pk_mul_f32 v[114:115], v[36:37], v[36:37]
	v_add_f32_e32 v6, v113, v6
	v_pk_mul_f32 v[112:113], v[78:79], v[78:79]
	v_add_f32_e32 v14, v111, v14
	v_add_f32_e32 v6, v114, v6
	v_add_f32_e32 v14, v112, v14
	v_add_f32_e32 v55, v115, v6
	v_pk_mul_f32 v[114:115], v[76:77], v[76:77]
	v_add_f32_e32 v14, v113, v14
	v_add_f32_e32 v14, v114, v14
	v_add_f32_e32 v14, v115, v14
	ds_bpermute_b32 v15, v101, v55
	ds_bpermute_b32 v16, v101, v14
	v_lshlrev_b32_e32 v6, 16, v2
	v_and_b32_e32 v7, 0xffff0000, v2
	v_lshlrev_b32_e32 v8, 16, v3
	s_waitcnt lgkmcnt(1)
	v_add_f32_e32 v15, v55, v15
	s_waitcnt lgkmcnt(0)
	v_add_f32_e32 v14, v14, v16
	ds_bpermute_b32 v16, v102, v15
	ds_bpermute_b32 v17, v102, v14
	v_and_b32_e32 v9, 0xffff0000, v3
	v_lshlrev_b32_e32 v10, 16, v4
	v_and_b32_e32 v11, 0xffff0000, v4
	s_waitcnt lgkmcnt(1)
	v_add_f32_e32 v15, v15, v16
	s_waitcnt lgkmcnt(0)
	v_add_f32_e32 v14, v14, v17
	ds_bpermute_b32 v16, v103, v15
	ds_bpermute_b32 v17, v103, v14
	v_lshlrev_b32_e32 v12, 16, v5
	v_and_b32_e32 v13, 0xffff0000, v5
	v_mov_b64_e32 v[2:3], v[148:149]
	v_mov_b64_e32 v[4:5], v[150:151]
	s_waitcnt lgkmcnt(1)
	v_add_f32_e32 v15, v15, v16
	s_waitcnt lgkmcnt(0)
	v_add_f32_e32 v14, v14, v17
	ds_bpermute_b32 v16, v104, v15
	ds_bpermute_b32 v17, v104, v14
	s_waitcnt lgkmcnt(1)
	v_add_f32_e32 v15, v15, v16
	s_waitcnt lgkmcnt(0)
	v_add_f32_e32 v14, v14, v17
	ds_bpermute_b32 v16, v105, v15
	ds_bpermute_b32 v17, v105, v14
	s_waitcnt lgkmcnt(1)
	v_add_f32_e32 v15, v15, v16
	s_waitcnt lgkmcnt(0)
	v_add_f32_e32 v14, v14, v17
	ds_bpermute_b32 v16, v106, v15
	ds_bpermute_b32 v17, v106, v14
	s_waitcnt lgkmcnt(1)
	v_add_f32_e32 v15, v15, v16
	s_waitcnt lgkmcnt(0)
; __device__ __forceinline__ unsigned pk2(float lo, float hi) { const pk_f32x2 v = {lo, hi}; const pk_bf16x2 b = __builtin_convertvector(v, pk_bf16x2); return __builtin_bit_cast(unsigned, b); }
; __device__ __forceinline__ float lane_xchg_(float v, int srclane) { return __builtin_bit_cast(float, __builtin_amdgcn_ds_bpermute(srclane << 2, __builtin_bit_cast(int, v))); }
; __device__ __forceinline__ void row_res(KP kp, int gpost_in, int layer, bool has_next, int wid0, int row0, int row1, int b0, int nb, int tailp, bool pooled) {
;     ...
;         for (int r = 0; r < 2; ++r) { const float rstd = 1.0f / sqrtf(ss[r] * (1.0f / DM) + NORM_EPS);
; #pragma unroll
;             for (int c = 0; c < 2; ++c) { const int col = c * 512 + lane * 8; const f32x4 ga = *(const f32x4*)(g_post + col), gb = *(const f32x4*)(g_post + col + 4);
; #pragma unroll
;                 for (int j = 0; j < 8; ++j) { h[r][c][j] += m[r][c][j] * rstd * (j < 4 ? ga[j & 3] : gb[j & 3]); s2[r] += h[r][c][j] * h[r][c][j]; } } }
;         if (has_next) {
; #pragma unroll
;             for (int o = 32; o > 0; o >>= 1) { const float a = lane_xchg_(s2[0], lane ^ o), b = lane_xchg_(s2[1], lane ^ o); s2[0] += a; s2[1] += b; }
; #pragma unroll
;             for (int r = 0; r < 2; ++r) { const int row = base + 8 * r; bf16* hp = hrow16(ws, row);
; #pragma unroll
;                 for (int c = 0; c < 2; ++c) { u32x4 hw; hw.x = pk2(h[r][c][0], h[r][c][1]); hw.y = pk2(h[r][c][2], h[r][c][3]); hw.z = pk2(h[r][c][4], h[r][c][5]); hw.w = pk2(h[r][c][6], h[r][c][7]);
;                     *(u32x4*)(hp + c * 512 + lane * 8) = hw; }
;                 if (lane == 0) rsd[row] = 1.0f / sqrtf(s2[r] * (1.0f / DM) + NORM_EPS); }
;         } else {
; #pragma unroll
;             for (int r = 0; r < 2; ++r) { const int row = base + 8 * r; const int b = row / LL, t = row - b * LL;
;                 if (t >= NMETA) { float* op = out + (((size_t)b * SEQ + (t - NMETA)) << 10);
; #pragma unroll
;                     for (int c = 0; c < 2; ++c) { const int col = c * 512 + lane * 8;
;                         __builtin_nontemporal_store((f32x4){h[r][c][0], h[r][c][1], h[r][c][2], h[r][c][3]}, (f32x4*)(op + col)); __builtin_nontemporal_store((f32x4){h[r][c][4], h[r][c][5], h[r][c][6], h[r][c][7]}, (f32x4*)(op + col + 4)); } } }
	v_add_f32_e32 v55, v14, v17
	v_fmamk_f32 v14, v15, 0x3a800000, v242
	v_cmp_gt_f32_e32 vcc, s80, v14
	v_mul_f32_e32 v15, 0x4f800000, v14
	v_fmamk_f32 v55, v55, 0x3a800000, v242
	v_cndmask_b32_e32 v14, v14, v15, vcc
	v_sqrt_f32_e32 v15, v14
	v_mul_f32_e32 v59, 0x4f800000, v55
	v_add_u32_e32 v16, -1, v15
	v_fma_f32 v17, -v16, v15, v14
	v_cmp_ge_f32_e64 s[4:5], 0, v17
	v_add_u32_e32 v17, 1, v15
	s_nop 0
	v_cndmask_b32_e64 v16, v15, v16, s[4:5]
	v_fma_f32 v15, -v17, v15, v14
	v_cmp_lt_f32_e64 s[4:5], 0, v15
	s_nop 1
	v_cndmask_b32_e64 v15, v16, v17, s[4:5]
	v_mul_f32_e32 v16, 0x37800000, v15
	v_cndmask_b32_e32 v15, v15, v16, vcc
	v_cmp_class_f32_e32 vcc, v14, v243
	s_nop 1
	v_cndmask_b32_e32 v14, v15, v14, vcc
	v_div_scale_f32 v15, s[4:5], v14, v14, 1.0
	v_rcp_f32_e32 v16, v15
	s_nop 0
	v_fma_f32 v17, -v15, v16, 1.0
	v_fmac_f32_e32 v16, v17, v16
	v_div_scale_f32 v17, vcc, 1.0, v14, 1.0
	v_mul_f32_e32 v18, v17, v16
	v_fma_f32 v19, -v15, v18, v17
	v_fmac_f32_e32 v18, v19, v16
	v_fma_f32 v15, -v15, v18, v17
	v_div_fmas_f32 v15, v15, v16, v18
	v_div_fixup_f32 v100, v15, v14, 1.0
	v_mov_b64_e32 v[14:15], v[156:157]
	v_mov_b64_e32 v[16:17], v[158:159]
	v_mov_b64_e32 v[18:19], v[152:153]
	v_mov_b64_e32 v[20:21], v[154:155]
	v_pk_mul_f32 v[22:23], v[22:23], v[100:101] op_sel_hi:[1,0]
	v_cmp_gt_f32_e32 vcc, s80, v55
	v_pk_mul_f32 v[30:31], v[30:31], v[100:101] op_sel_hi:[1,0]
	v_pk_mul_f32 v[32:33], v[32:33], v[100:101] op_sel_hi:[1,0]
	v_cndmask_b32_e32 v55, v55, v59, vcc
	v_sqrt_f32_e32 v59, v55
	v_pk_mul_f32 v[34:35], v[34:35], v[100:101] op_sel_hi:[1,0]
	v_pk_mul_f32 v[36:37], v[36:37], v[100:101] op_sel_hi:[1,0]
	v_add_u32_e32 v65, -1, v59
	v_pk_fma_f32 v[6:7], v[18:19], v[22:23], v[6:7]
	v_pk_mul_f32 v[22:23], v[24:25], v[100:101] op_sel_hi:[1,0]
	s_nop 0
	v_pk_fma_f32 v[8:9], v[20:21], v[22:23], v[8:9]
	v_pk_mul_f32 v[22:23], v[26:27], v[100:101] op_sel_hi:[1,0]
	s_nop 0
	v_pk_fma_f32 v[10:11], v[14:15], v[22:23], v[10:11]
	v_pk_mul_f32 v[22:23], v[28:29], v[100:101] op_sel_hi:[1,0]
	s_nop 0
	v_pk_fma_f32 v[12:13], v[16:17], v[22:23], v[12:13]
	v_mov_b64_e32 v[22:23], v[164:165]
	v_mov_b64_e32 v[24:25], v[166:167]
	v_mov_b64_e32 v[26:27], v[160:161]
	v_mov_b64_e32 v[28:29], v[162:163]
	v_pk_fma_f32 v[34:35], v[22:23], v[34:35], v[98:99]
	v_pk_fma_f32 v[30:31], v[26:27], v[30:31], v[92:93]
	v_fma_f32 v92, -v65, v59, v55
	v_cmp_ge_f32_e64 s[4:5], 0, v92
	v_add_u32_e32 v92, 1, v59
	v_pk_fma_f32 v[32:33], v[28:29], v[32:33], v[94:95]
	v_cndmask_b32_e64 v65, v59, v65, s[4:5]
	v_fma_f32 v59, -v92, v59, v55
	v_cmp_lt_f32_e64 s[4:5], 0, v59
	v_pk_fma_f32 v[36:37], v[24:25], v[36:37], v[96:97]
	s_nop 0
	v_cndmask_b32_e64 v59, v65, v92, s[4:5]
	v_mul_f32_e32 v65, 0x37800000, v59
	v_cndmask_b32_e32 v59, v59, v65, vcc
	v_cmp_class_f32_e32 vcc, v55, v243
	s_nop 1
	v_cndmask_b32_e32 v55, v59, v55, vcc
	v_div_scale_f32 v59, s[4:5], v55, v55, 1.0
	v_rcp_f32_e32 v65, v59
	s_mov_b64 s[4:5], -1
	v_fma_f32 v92, -v59, v65, 1.0
	v_fmac_f32_e32 v65, v92, v65
	v_div_scale_f32 v92, vcc, 1.0, v55, 1.0
	v_mul_f32_e32 v93, v92, v65
	v_fma_f32 v94, -v59, v93, v92
	v_fmac_f32_e32 v93, v94, v65
	v_fma_f32 v59, -v59, v93, v92
	v_div_fmas_f32 v59, v59, v65, v93
	v_div_fixup_f32 v92, v59, v55, 1.0
	v_pk_mul_f32 v[68:69], v[68:69], v[92:93] op_sel_hi:[1,0]
	s_andn2_b64 vcc, exec, s[34:35]
	v_pk_fma_f32 v[18:19], v[18:19], v[68:69], v[84:85]
	v_pk_mul_f32 v[68:69], v[70:71], v[92:93] op_sel_hi:[1,0]
	v_pk_mul_f32 v[70:71], v[82:83], v[92:93] op_sel_hi:[1,0]
	v_pk_fma_f32 v[20:21], v[20:21], v[68:69], v[86:87]
	v_pk_mul_f32 v[68:69], v[72:73], v[92:93] op_sel_hi:[1,0]
	s_nop 0
	v_pk_fma_f32 v[14:15], v[14:15], v[68:69], v[88:89]
	v_pk_mul_f32 v[68:69], v[74:75], v[92:93] op_sel_hi:[1,0]
	s_nop 0
	v_pk_fma_f32 v[16:17], v[16:17], v[68:69], v[90:91]
	v_lshlrev_b32_e32 v68, 16, v2
	v_and_b32_e32 v69, 0xffff0000, v2
	v_pk_fma_f32 v[26:27], v[26:27], v[70:71], v[68:69]
	v_lshlrev_b32_e32 v2, 16, v3
	v_and_b32_e32 v3, 0xffff0000, v3
	v_pk_mul_f32 v[68:69], v[80:81], v[92:93] op_sel_hi:[1,0]
	s_nop 0
	v_pk_fma_f32 v[28:29], v[28:29], v[68:69], v[2:3]
	v_lshlrev_b32_e32 v2, 16, v4
	v_and_b32_e32 v3, 0xffff0000, v4
	v_pk_mul_f32 v[68:69], v[78:79], v[92:93] op_sel_hi:[1,0]
	v_lshlrev_b32_e32 v4, 16, v5
	v_pk_fma_f32 v[2:3], v[22:23], v[68:69], v[2:3]
	v_and_b32_e32 v5, 0xffff0000, v5
	v_pk_mul_f32 v[22:23], v[76:77], v[92:93] op_sel_hi:[1,0]
	s_nop 0
	v_pk_fma_f32 v[4:5], v[24:25], v[22:23], v[4:5]
	s_cmp_eq_u64 s[78:79], 0
	s_cbranch_scc1 .Lrp_nocopy
	s_waitcnt vmcnt(0)
	v_mov_b64_e32 v[120:121], v[174:175]
	v_mov_b64_e32 v[122:123], v[176:177]
	v_mov_b64_e32 v[124:125], v[178:179]
	v_mov_b64_e32 v[126:127], v[180:181]
	v_mov_b64_e32 v[128:129], v[182:183]
	v_mov_b64_e32 v[130:131], v[184:185]
	v_mov_b64_e32 v[132:133], v[186:187]
	v_mov_b64_e32 v[134:135], v[188:189]
	v_mov_b64_e32 v[136:137], v[190:191]
	v_mov_b64_e32 v[138:139], v[192:193]
	v_mov_b64_e32 v[140:141], v[194:195]
	v_mov_b64_e32 v[142:143], v[196:197]
	v_mov_b64_e32 v[144:145], v[198:199]
	v_mov_b64_e32 v[146:147], v[200:201]
	v_mov_b64_e32 v[148:149], v[202:203]
	v_mov_b64_e32 v[150:151], v[204:205]
.Lrp_nocopy:
	s_cbranch_vccnz .LBB0_816
	v_mad_i32_i24 v23, v58, s84, v38
	v_cmp_lt_i32_e32 vcc, 15, v23
	v_lshlrev_b32_e32 v22, 2, v40
	s_and_saveexec_b64 s[4:5], vcc
	s_cbranch_execz .LBB0_813
	v_ashrrev_i32_e32 v59, 31, v58
	v_add_u32_e32 v24, -16, v23
	v_mov_b32_e32 v25, v0
	v_lshlrev_b64 v[58:59], 23, v[58:59]
	v_lshl_add_u64 v[58:59], s[8:9], 0, v[58:59]
	v_lshlrev_b64 v[24:25], 12, v[24:25]
	v_lshl_add_u64 v[24:25], v[58:59], 0, v[24:25]
	v_mov_b32_e32 v23, v0
	v_lshl_add_u64 v[24:25], v[24:25], 0, v[22:23]
	global_store_dwordx4 v[24:25], v[6:9], off nt
	global_store_dwordx4 v[24:25], v[10:13], off offset:16 nt
	global_store_dwordx4 v[24:25], v[30:33], off offset:2048 nt
	global_store_dwordx4 v[24:25], v[34:37], off offset:2064 nt

; __device__ __forceinline__ bf16* hrow16(unsigned char* ws, int r) { return (bf16*)(ws + WS_H16) + ((size_t)r << 10); }
; __device__ __forceinline__ void row_res(KP kp, int gpost_in, int layer, bool has_next, int wid0, int row0, int row1, int b0, int nb, int tailp, bool pooled) {
;     ...
;     for (int base = row0 + ((int)blockIdx.x - b0) * 16 + wid; base < row1; base += nb * 16) {
;         float m[2][2][8], h[2][2][8]; float ss[2] = {0.f, 0.f};
; #pragma unroll
;         for (int r = 0; r < 2; ++r) { const int row = base + 8 * r; bf16* hp = hrow16(ws, row);
; #pragma unroll
;             for (int c = 0; c < 2; ++c) {
;                 if (tailp) { const bf16* t0 = (const bf16*)(ws + WS_MXT) + (size_t)(row - 128 * 256) * DM + c * 512 + lane * 8; unpack8(*(const u32x4*)t0, m[r][c]);
;                     for (int q = 1; q < tailp; ++q) { float m2[8]; unpack8(*(const u32x4*)(t0 + (size_t)q * 256 * 1024), m2);
; #pragma unroll
;                         for (int j = 0; j < 8; ++j) m[r][c][j] += m2[j]; } }
;                 else if (pooled) { const int t = row % LL, win = 2 << (c * 2 + (lane >> 5)), cnt = (t + 1) < win ? (t + 1) : win; const bf16* zp = MX + (size_t)row * DM + c * 512 + lane * 8;
;                     float z0[8], sum[8]; unpack8(*(const u32x4*)zp, z0);
; #pragma unroll
;                     for (int j = 0; j < 8; ++j) sum[j] = z0[j];
;                     for (int d = 1; d < cnt; ++d) { float zd[8]; unpack8(*(const u32x4*)(zp - (size_t)d * DM), zd);
; #pragma unroll
;                         for (int j = 0; j < 8; ++j) sum[j] += zd[j]; }
;                     const float inv = 1.0f / (float)cnt;
; #pragma unroll
;                     for (int j = 0; j < 8; ++j) m[r][c][j] = sum[j] * inv - z0[j]; }
;                 else { const u32x4 w = *(const u32x4*)(MX + (size_t)row * DM + c * 512 + lane * 8); unpack8(w, m[r][c]); }
;                 unpack8(*(const u32x4*)(hp + c * 512 + lane * 8), h[r][c]);
; #pragma unroll
;                 for (int j = 0; j < 8; ++j) ss[r] += m[r][c][j] * m[r][c][j]; } }
; #pragma unroll
;         for (int o = 32; o > 0; o >>= 1) { const float a = lane_xchg_(ss[0], lane ^ o), b = lane_xchg_(ss[1], lane ^ o); ss[0] += a; ss[1] += b; }
;         float s2[2] = {0.f, 0.f};
; #pragma unroll
;         for (int r = 0; r < 2; ++r) { const float rstd = 1.0f / sqrtf(ss[r] * (1.0f / DM) + NORM_EPS);
; #pragma unroll
.LBB0_821:
	s_waitcnt vmcnt(0)
	s_or_b64 exec, exec, s[44:45]
	s_mov_b64 s[2:3], 0
	s_movk_i32 s63, 0x50
	s_movk_i32 s90, 0xc00
	s_mov_b64 s[92:93], 0x48080
